# GEMM loop: m0-to-LDS-DMA wait states filled with a fragment ds_read of the same cluster instead of s_nop (6 nops removed)
# speedup vs baseline: 1.0011x; 1.0011x over previous
; #define PG8_STAGE(bufoff, gbase, voff) do { _Pragma("unroll") for (int _i = 0; _i < 2; ++_i) \
;         __builtin_amdgcn_global_load_lds((const unsigned*)((const char*)(gbase) + (voff)[_i]), (LAS unsigned*)(lds + (bufoff) + ldsw + _i * 8192), 16, 0, 0); } while (0)
; #define PG8_LDA(dst, b, h) do { _Pragma("unroll") for (int m = 0; m < 4; ++m) _Pragma("unroll") for (int k = 0; k < 2; ++k) dst[m][k] = *(const LAS h16x8*)(lds + PG8_SA(b, h) + aoff + m * 2048 + k * 1024); } while (0)
; #define PG8_LDB(dst, b, h) do { _Pragma("unroll") for (int n = 0; n < 2; ++n) _Pragma("unroll") for (int k = 0; k < 2; ++k) dst[n][k] = *(const LAS h16x8*)(lds + PG8_SB(b, h) + boff + n * 2048 + k * 1024); } while (0)
; #define PG8_MMA(ai, bj, At, Bt) do { __builtin_amdgcn_s_setprio(1); _Pragma("unroll") for (int m = 0; m < 4; ++m) _Pragma("unroll") for (int n = 0; n < 2; ++n) _Pragma("unroll") for (int k = 0; k < 2; ++k) \
;         acc[ai][bj][m][n] = __builtin_amdgcn_mfma_f32_16x16x32_f16(Bt[n][k], At[m][k], acc[ai][bj][m][n], 0, 0, 0); __builtin_amdgcn_s_setprio(0); } while (0)
; #define PG8_WAIT_L(n) asm volatile("s_waitcnt lgkmcnt(" #n ")" ::: "memory")
; #define PG8_BAR __builtin_amdgcn_s_barrier()
; #define PG8_SCHED __builtin_amdgcn_sched_barrier(0)
; __device__ __forceinline__ void gemm_phase(LAS unsigned char* lds, const Gemm g, const StaticOrder& S, const Epi& E) {
;     ...
;             const bool last = (t == nt - 2);
;             const char* a1 = cA + PG8_KOFF(t + 1);
;             const char* a2 = last ? nA : cA + PG8_KOFF(t + 2); const char* b2 = last ? nB : cB + (size_t)(t + 2) * kstep;
;             const char* a3 = a2 + kstep; const char* b3 = b2 + kstep;
;             PG8_LDB(B0, 0, 0); PG8_SCHED; PG8_LDA(At, 0, 0); PG8_STAGE(PG8_SA(1, 1), a1 + hstepA, voffA);
;             PG8_WAIT_L(8); PG8_BAR; PG8_WAIT_L(0); PG8_MMA(0, 0, At, B0); PG8_BAR; PG8_SCHED;
;             PG8_LDB(B1, 0, 1); PG8_STAGE(PG8_SB(0, 0), b2, voffB);
;             PG8_BAR; PG8_WAIT_L(0); PG8_MMA(0, 1, At, B1); PG8_BAR;
;             PG8_LDA(At, 0, 1); PG8_STAGE(PG8_SA(0, 0), a2, voffA);
;             PG8_BAR; PG8_WAIT_L(0); PG8_MMA(1, 0, At, B0); PG8_BAR; PG8_SCHED;
.Lprio_skip:
.LBB0_762:
	s_cmp_gt_u32 s34, 15
	s_cselect_b64 s[36:37], -1, 0
	s_and_b64 s[36:37], s[6:7], s[36:37]
	s_and_b64 s[36:37], s[36:37], exec
	s_cselect_b32 s42, 0xfffff000, 0
	s_cselect_b32 s43, -1, 0
	s_add_i32 s38, s34, 2
	s_cmp_gt_u32 s34, 13
	s_cselect_b64 s[36:37], -1, 0
	s_and_b64 s[36:37], s[6:7], s[36:37]
	s_and_b64 s[36:37], s[36:37], exec
	s_cselect_b32 s36, 0xfffff000, 0
	s_cselect_b32 s35, -1, 0
	s_add_u32 s36, s0, s36
	s_addc_u32 s35, s1, s35
	s_add_u32 s36, s36, 0x80
	s_addc_u32 s35, s35, 0
	ds_read_b128 v[128:131], v224
	ds_read_b128 v[132:135], v224 offset:1024
	ds_read_b128 v[136:139], v224 offset:2048
	ds_read_b128 v[140:143], v224 offset:3072
	s_cmp_eq_u32 s66, s34
	s_cselect_b32 s34, s4, s36
	s_cselect_b32 s35, s5, s35
	s_cselect_b32 s37, s29, s33
	s_cselect_b32 s36, s28, s27
	s_add_u32 s86, s0, s42
	s_addc_u32 s87, s1, s43
	s_add_i32 m0, s58, 0xc000
	ds_read_b128 v[144:147], v239
	ds_read_b128 v[148:151], v239 offset:1024
	ds_read_b128 v[152:155], v239 offset:2048
	ds_read_b128 v[156:159], v239 offset:3072
	ds_read_b128 v[160:163], v239 offset:4096
	ds_read_b128 v[164:167], v239 offset:5120
	ds_read_b128 v[168:171], v239 offset:6144
	global_load_lds_dwordx4 v212, s[86:87]
	s_add_i32 m0, s58, 0xe000
	ds_read_b128 v[172:175], v239 offset:7168
	global_load_lds_dwordx4 v214, s[86:87]
	s_waitcnt lgkmcnt(8)
	s_barrier
	s_waitcnt lgkmcnt(0)
	v_mfma_f32_16x16x32_f16 v[124:127], v[128:131], v[144:147], v[124:127]
	v_mfma_f32_16x16x32_f16 v[120:123], v[136:139], v[144:147], v[120:123]
	v_mfma_f32_16x16x32_f16 v[108:111], v[128:131], v[152:155], v[108:111]
	v_mfma_f32_16x16x32_f16 v[104:107], v[136:139], v[152:155], v[104:107]
	v_mfma_f32_16x16x32_f16 v[92:95], v[128:131], v[160:163], v[92:95]
	v_mfma_f32_16x16x32_f16 v[88:91], v[136:139], v[160:163], v[88:91]
	v_mfma_f32_16x16x32_f16 v[76:79], v[128:131], v[168:171], v[76:79]
	v_mfma_f32_16x16x32_f16 v[72:75], v[136:139], v[168:171], v[72:75]
	v_mfma_f32_16x16x32_f16 v[124:127], v[132:135], v[148:151], v[124:127]
	v_mfma_f32_16x16x32_f16 v[120:123], v[140:143], v[148:151], v[120:123]
	v_mfma_f32_16x16x32_f16 v[108:111], v[132:135], v[156:159], v[108:111]
	v_mfma_f32_16x16x32_f16 v[104:107], v[140:143], v[156:159], v[104:107]
	v_mfma_f32_16x16x32_f16 v[92:95], v[132:135], v[164:167], v[92:95]
	v_mfma_f32_16x16x32_f16 v[88:91], v[140:143], v[164:167], v[88:91]
	v_mfma_f32_16x16x32_f16 v[76:79], v[132:135], v[172:175], v[76:79]
	v_mfma_f32_16x16x32_f16 v[72:75], v[140:143], v[172:175], v[72:75]
	s_barrier
	s_add_u32 s86, s36, 0x80
	s_addc_u32 s87, s37, 0
	s_add_i32 m0, s31, 0x10000
	ds_read_b128 v[176:179], v225
	ds_read_b128 v[180:183], v225 offset:1024
	ds_read_b128 v[184:187], v225 offset:2048
	global_load_lds_dwordx4 v206, s[36:37]
	s_add_i32 m0, s31, 0x12000
	ds_read_b128 v[188:191], v225 offset:3072
	global_load_lds_dwordx4 v210, s[36:37]
	s_barrier
	s_waitcnt lgkmcnt(0)
	v_mfma_f32_16x16x32_f16 v[116:119], v[176:179], v[144:147], v[116:119]
	v_mfma_f32_16x16x32_f16 v[112:115], v[184:187], v[144:147], v[112:115]
	v_mfma_f32_16x16x32_f16 v[100:103], v[176:179], v[152:155], v[100:103]
	v_mfma_f32_16x16x32_f16 v[96:99], v[184:187], v[152:155], v[96:99]
	v_mfma_f32_16x16x32_f16 v[84:87], v[176:179], v[160:163], v[84:87]
	v_mfma_f32_16x16x32_f16 v[80:83], v[184:187], v[160:163], v[80:83]
	v_mfma_f32_16x16x32_f16 v[68:71], v[176:179], v[168:171], v[68:71]
	v_mfma_f32_16x16x32_f16 v[64:67], v[184:187], v[168:171], v[64:67]
	v_mfma_f32_16x16x32_f16 v[116:119], v[180:183], v[148:151], v[116:119]
	v_mfma_f32_16x16x32_f16 v[112:115], v[188:191], v[148:151], v[112:115]
	v_mfma_f32_16x16x32_f16 v[100:103], v[180:183], v[156:159], v[100:103]
	v_mfma_f32_16x16x32_f16 v[96:99], v[188:191], v[156:159], v[96:99]
	v_mfma_f32_16x16x32_f16 v[84:87], v[180:183], v[164:167], v[84:87]
	v_mfma_f32_16x16x32_f16 v[80:83], v[188:191], v[164:167], v[80:83]
	v_mfma_f32_16x16x32_f16 v[68:71], v[180:183], v[172:175], v[68:71]
	v_mfma_f32_16x16x32_f16 v[64:67], v[188:191], v[172:175], v[64:67]
	s_mov_b32 m0, s58
	s_add_u32 s88, s34, 0x80
	s_addc_u32 s89, s35, 0
	s_barrier
	ds_read_b128 v[144:147], v239 offset:16384
	ds_read_b128 v[148:151], v239 offset:17408
	ds_read_b128 v[152:155], v239 offset:18432
	ds_read_b128 v[156:159], v239 offset:19456
	ds_read_b128 v[160:163], v239 offset:20480
	ds_read_b128 v[164:167], v239 offset:21504
	ds_read_b128 v[168:171], v239 offset:22528
	global_load_lds_dwordx4 v204, s[34:35]
	s_mov_b32 m0, s59
	ds_read_b128 v[172:175], v239 offset:23552
	global_load_lds_dwordx4 v208, s[34:35]
	s_barrier
	s_waitcnt lgkmcnt(0)
	v_mfma_f32_16x16x32_f16 v[60:63], v[128:131], v[144:147], v[60:63]
	v_mfma_f32_16x16x32_f16 v[56:59], v[136:139], v[144:147], v[56:59]
	v_mfma_f32_16x16x32_f16 v[44:47], v[128:131], v[152:155], v[44:47]
	v_mfma_f32_16x16x32_f16 v[40:43], v[136:139], v[152:155], v[40:43]
	v_mfma_f32_16x16x32_f16 v[28:31], v[128:131], v[160:163], v[28:31]
	v_mfma_f32_16x16x32_f16 v[24:27], v[136:139], v[160:163], v[24:27]
	v_mfma_f32_16x16x32_f16 v[12:15], v[128:131], v[168:171], v[12:15]
	v_mfma_f32_16x16x32_f16 v[8:11], v[136:139], v[168:171], v[8:11]
	v_mfma_f32_16x16x32_f16 v[60:63], v[132:135], v[148:151], v[60:63]
	v_mfma_f32_16x16x32_f16 v[56:59], v[140:143], v[148:151], v[56:59]
	v_mfma_f32_16x16x32_f16 v[44:47], v[132:135], v[156:159], v[44:47]
	v_mfma_f32_16x16x32_f16 v[40:43], v[140:143], v[156:159], v[40:43]
	v_mfma_f32_16x16x32_f16 v[28:31], v[132:135], v[164:167], v[28:31]
	v_mfma_f32_16x16x32_f16 v[24:27], v[140:143], v[164:167], v[24:27]
	v_mfma_f32_16x16x32_f16 v[12:15], v[132:135], v[172:175], v[12:15]
	v_mfma_f32_16x16x32_f16 v[8:11], v[140:143], v[172:175], v[8:11]
	s_barrier
; #define PG8_STAGE(bufoff, gbase, voff) do { _Pragma("unroll") for (int _i = 0; _i < 2; ++_i) \
;         __builtin_amdgcn_global_load_lds((const unsigned*)((const char*)(gbase) + (voff)[_i]), (LAS unsigned*)(lds + (bufoff) + ldsw + _i * 8192), 16, 0, 0); } while (0)
; #define PG8_LDA(dst, b, h) do { _Pragma("unroll") for (int m = 0; m < 4; ++m) _Pragma("unroll") for (int k = 0; k < 2; ++k) dst[m][k] = *(const LAS h16x8*)(lds + PG8_SA(b, h) + aoff + m * 2048 + k * 1024); } while (0)
; #define PG8_LDB(dst, b, h) do { _Pragma("unroll") for (int n = 0; n < 2; ++n) _Pragma("unroll") for (int k = 0; k < 2; ++k) dst[n][k] = *(const LAS h16x8*)(lds + PG8_SB(b, h) + boff + n * 2048 + k * 1024); } while (0)
; #define PG8_MMA(ai, bj, At, Bt) do { __builtin_amdgcn_s_setprio(1); _Pragma("unroll") for (int m = 0; m < 4; ++m) _Pragma("unroll") for (int n = 0; n < 2; ++n) _Pragma("unroll") for (int k = 0; k < 2; ++k) \
;         acc[ai][bj][m][n] = __builtin_amdgcn_mfma_f32_16x16x32_f16(Bt[n][k], At[m][k], acc[ai][bj][m][n], 0, 0, 0); __builtin_amdgcn_s_setprio(0); } while (0)
; #define PG8_WAIT_V(n) asm volatile("s_waitcnt vmcnt(" #n ")" ::: "memory")
; #define PG8_WAIT_L(n) asm volatile("s_waitcnt lgkmcnt(" #n ")" ::: "memory")
; #define PG8_BAR __builtin_amdgcn_s_barrier()
; #define PG8_SCHED __builtin_amdgcn_sched_barrier(0)
; __device__ __forceinline__ void gemm_phase(LAS unsigned char* lds, const Gemm g, const StaticOrder& S, const Epi& E) {
;     ...
;             PG8_STAGE(PG8_SB(0, 1), b2 + hstepB, voffB);
;             PG8_WAIT_V(6); PG8_BAR; PG8_MMA(1, 1, At, B1); PG8_BAR;
;             PG8_LDB(B0, 1, 0); PG8_SCHED; PG8_LDA(At, 1, 0); PG8_STAGE(PG8_SA(0, 1), a2 + hstepA, voffA);
;             PG8_WAIT_L(8); PG8_BAR; PG8_WAIT_L(0); PG8_MMA(0, 0, At, B0); PG8_BAR; PG8_SCHED;
;             PG8_LDB(B1, 1, 1); PG8_STAGE(PG8_SB(1, 0), b3, voffB);
	s_add_u32 s36, s36, s18
	s_addc_u32 s37, s37, s19
	s_add_u32 s96, s36, 0x80
	s_addc_u32 s97, s37, 0
	s_add_i32 m0, s31, 0x14000
	s_nop 0
	global_load_lds_dwordx4 v206, s[36:37]
	s_add_i32 m0, s31, 0x16000
	s_nop 0
	global_load_lds_dwordx4 v210, s[36:37]
	s_waitcnt vmcnt(6)
	s_barrier
	v_mfma_f32_16x16x32_f16 v[52:55], v[176:179], v[144:147], v[52:55]
	v_mfma_f32_16x16x32_f16 v[48:51], v[184:187], v[144:147], v[48:51]
	v_mfma_f32_16x16x32_f16 v[36:39], v[176:179], v[152:155], v[36:39]
	v_mfma_f32_16x16x32_f16 v[32:35], v[184:187], v[152:155], v[32:35]
	v_mfma_f32_16x16x32_f16 v[20:23], v[176:179], v[160:163], v[20:23]
	v_mfma_f32_16x16x32_f16 v[16:19], v[184:187], v[160:163], v[16:19]
	v_mfma_f32_16x16x32_f16 v[4:7], v[176:179], v[168:171], v[4:7]
	v_mfma_f32_16x16x32_f16 v[0:3], v[184:187], v[168:171], v[0:3]
	v_mfma_f32_16x16x32_f16 v[52:55], v[180:183], v[148:151], v[52:55]
	v_mfma_f32_16x16x32_f16 v[48:51], v[188:191], v[148:151], v[48:51]
	v_mfma_f32_16x16x32_f16 v[36:39], v[180:183], v[156:159], v[36:39]
	v_mfma_f32_16x16x32_f16 v[32:35], v[188:191], v[156:159], v[32:35]
	v_mfma_f32_16x16x32_f16 v[20:23], v[180:183], v[164:167], v[20:23]
	v_mfma_f32_16x16x32_f16 v[16:19], v[188:191], v[164:167], v[16:19]
	v_mfma_f32_16x16x32_f16 v[4:7], v[180:183], v[172:175], v[4:7]
	v_mfma_f32_16x16x32_f16 v[0:3], v[188:191], v[172:175], v[0:3]
	s_barrier
	ds_read_b128 v[128:131], v241
	ds_read_b128 v[132:135], v241 offset:1024
	ds_read_b128 v[136:139], v241 offset:2048
	ds_read_b128 v[140:143], v241 offset:3072
	s_add_u32 s34, s34, s16
	s_addc_u32 s35, s35, s17
	s_mov_b32 m0, s60
	ds_read_b128 v[144:147], v239 offset:32768
	ds_read_b128 v[148:151], v239 offset:33792
	ds_read_b128 v[152:155], v239 offset:34816
	ds_read_b128 v[156:159], v239 offset:35840
	ds_read_b128 v[160:163], v239 offset:36864
	ds_read_b128 v[164:167], v239 offset:37888
	ds_read_b128 v[168:171], v239 offset:38912
	global_load_lds_dwordx4 v204, s[34:35]
	s_mov_b32 m0, s61
	ds_read_b128 v[172:175], v239 offset:39936
	global_load_lds_dwordx4 v208, s[34:35]
	s_waitcnt lgkmcnt(8)
	s_barrier
	s_waitcnt lgkmcnt(0)
	v_mfma_f32_16x16x32_f16 v[124:127], v[128:131], v[144:147], v[124:127]
	v_mfma_f32_16x16x32_f16 v[120:123], v[136:139], v[144:147], v[120:123]
	v_mfma_f32_16x16x32_f16 v[108:111], v[128:131], v[152:155], v[108:111]
	v_mfma_f32_16x16x32_f16 v[104:107], v[136:139], v[152:155], v[104:107]
	v_mfma_f32_16x16x32_f16 v[92:95], v[128:131], v[160:163], v[92:95]
	v_mfma_f32_16x16x32_f16 v[88:91], v[136:139], v[160:163], v[88:91]
	v_mfma_f32_16x16x32_f16 v[76:79], v[128:131], v[168:171], v[76:79]
	v_mfma_f32_16x16x32_f16 v[72:75], v[136:139], v[168:171], v[72:75]
	v_mfma_f32_16x16x32_f16 v[124:127], v[132:135], v[148:151], v[124:127]
	v_mfma_f32_16x16x32_f16 v[120:123], v[140:143], v[148:151], v[120:123]
	v_mfma_f32_16x16x32_f16 v[108:111], v[132:135], v[156:159], v[108:111]
	v_mfma_f32_16x16x32_f16 v[104:107], v[140:143], v[156:159], v[104:107]
	v_mfma_f32_16x16x32_f16 v[92:95], v[132:135], v[164:167], v[92:95]
	v_mfma_f32_16x16x32_f16 v[88:91], v[140:143], v[164:167], v[88:91]
	v_mfma_f32_16x16x32_f16 v[76:79], v[132:135], v[172:175], v[76:79]
	v_mfma_f32_16x16x32_f16 v[72:75], v[140:143], v[172:175], v[72:75]
	s_barrier
	s_add_i32 m0, s31, 0x18000
	ds_read_b128 v[176:179], v248
	ds_read_b128 v[180:183], v248 offset:1024
	ds_read_b128 v[184:187], v248 offset:2048
	global_load_lds_dwordx4 v206, s[86:87]
	s_add_i32 m0, s31, 0x1a000
	ds_read_b128 v[188:191], v248 offset:3072
	global_load_lds_dwordx4 v210, s[86:87]
	s_barrier
; #define PG8_STAGE(bufoff, gbase, voff) do { _Pragma("unroll") for (int _i = 0; _i < 2; ++_i) \
;         __builtin_amdgcn_global_load_lds((const unsigned*)((const char*)(gbase) + (voff)[_i]), (LAS unsigned*)(lds + (bufoff) + ldsw + _i * 8192), 16, 0, 0); } while (0)
; #define PG8_LDA(dst, b, h) do { _Pragma("unroll") for (int m = 0; m < 4; ++m) _Pragma("unroll") for (int k = 0; k < 2; ++k) dst[m][k] = *(const LAS h16x8*)(lds + PG8_SA(b, h) + aoff + m * 2048 + k * 1024); } while (0)
; #define PG8_MMA(ai, bj, At, Bt) do { __builtin_amdgcn_s_setprio(1); _Pragma("unroll") for (int m = 0; m < 4; ++m) _Pragma("unroll") for (int n = 0; n < 2; ++n) _Pragma("unroll") for (int k = 0; k < 2; ++k) \
;         acc[ai][bj][m][n] = __builtin_amdgcn_mfma_f32_16x16x32_f16(Bt[n][k], At[m][k], acc[ai][bj][m][n], 0, 0, 0); __builtin_amdgcn_s_setprio(0); } while (0)
; #define PG8_WAIT_V(n) asm volatile("s_waitcnt vmcnt(" #n ")" ::: "memory")
; #define PG8_WAIT_L(n) asm volatile("s_waitcnt lgkmcnt(" #n ")" ::: "memory")
; #define PG8_BAR __builtin_amdgcn_s_barrier()
; #define PG8_SCHED __builtin_amdgcn_sched_barrier(0)
; __device__ __forceinline__ void gemm_phase(LAS unsigned char* lds, const Gemm g, const StaticOrder& S, const Epi& E) {
;     ...
;             PG8_BAR; PG8_WAIT_L(0); PG8_MMA(0, 1, At, B1); PG8_BAR;
;             PG8_LDA(At, 1, 1); PG8_STAGE(PG8_SA(1, 0), a3, voffA);
;             PG8_BAR; PG8_WAIT_L(0); PG8_MMA(1, 0, At, B0); PG8_BAR; PG8_SCHED;
;             PG8_STAGE(PG8_SB(1, 1), b3 + hstepB, voffB);
;             PG8_WAIT_V(6); PG8_BAR; PG8_MMA(1, 1, At, B1); PG8_BAR;
;         }
;         E(acc, cur, wr, wc, fr, fq);
	s_waitcnt lgkmcnt(0)
	v_mfma_f32_16x16x32_f16 v[116:119], v[176:179], v[144:147], v[116:119]
	v_mfma_f32_16x16x32_f16 v[112:115], v[184:187], v[144:147], v[112:115]
	v_mfma_f32_16x16x32_f16 v[100:103], v[176:179], v[152:155], v[100:103]
	v_mfma_f32_16x16x32_f16 v[96:99], v[184:187], v[152:155], v[96:99]
	v_mfma_f32_16x16x32_f16 v[84:87], v[176:179], v[160:163], v[84:87]
	v_mfma_f32_16x16x32_f16 v[80:83], v[184:187], v[160:163], v[80:83]
	v_mfma_f32_16x16x32_f16 v[68:71], v[176:179], v[168:171], v[68:71]
	v_mfma_f32_16x16x32_f16 v[64:67], v[184:187], v[168:171], v[64:67]
	v_mfma_f32_16x16x32_f16 v[116:119], v[180:183], v[148:151], v[116:119]
	v_mfma_f32_16x16x32_f16 v[112:115], v[188:191], v[148:151], v[112:115]
	v_mfma_f32_16x16x32_f16 v[100:103], v[180:183], v[156:159], v[100:103]
	v_mfma_f32_16x16x32_f16 v[96:99], v[188:191], v[156:159], v[96:99]
	v_mfma_f32_16x16x32_f16 v[84:87], v[180:183], v[164:167], v[84:87]
	v_mfma_f32_16x16x32_f16 v[80:83], v[188:191], v[164:167], v[80:83]
	v_mfma_f32_16x16x32_f16 v[68:71], v[180:183], v[172:175], v[68:71]
	v_mfma_f32_16x16x32_f16 v[64:67], v[188:191], v[172:175], v[64:67]
	s_mov_b32 m0, s62
	s_barrier
	ds_read_b128 v[144:147], v239 offset:49152
	ds_read_b128 v[148:151], v239 offset:50176
	ds_read_b128 v[152:155], v239 offset:51200
	ds_read_b128 v[156:159], v239 offset:52224
	ds_read_b128 v[160:163], v239 offset:53248
	ds_read_b128 v[164:167], v239 offset:54272
	ds_read_b128 v[168:171], v239 offset:55296
	global_load_lds_dwordx4 v204, s[88:89]
	s_mov_b32 m0, s63
	ds_read_b128 v[172:175], v239 offset:56320
	global_load_lds_dwordx4 v208, s[88:89]
	s_barrier
	s_waitcnt lgkmcnt(0)
	v_mfma_f32_16x16x32_f16 v[60:63], v[128:131], v[144:147], v[60:63]
	v_mfma_f32_16x16x32_f16 v[56:59], v[136:139], v[144:147], v[56:59]
	v_mfma_f32_16x16x32_f16 v[44:47], v[128:131], v[152:155], v[44:47]
	v_mfma_f32_16x16x32_f16 v[40:43], v[136:139], v[152:155], v[40:43]
	v_mfma_f32_16x16x32_f16 v[28:31], v[128:131], v[160:163], v[28:31]
	v_mfma_f32_16x16x32_f16 v[24:27], v[136:139], v[160:163], v[24:27]
	v_mfma_f32_16x16x32_f16 v[12:15], v[128:131], v[168:171], v[12:15]
	v_mfma_f32_16x16x32_f16 v[8:11], v[136:139], v[168:171], v[8:11]
	v_mfma_f32_16x16x32_f16 v[60:63], v[132:135], v[148:151], v[60:63]
	v_mfma_f32_16x16x32_f16 v[56:59], v[140:143], v[148:151], v[56:59]
	v_mfma_f32_16x16x32_f16 v[44:47], v[132:135], v[156:159], v[44:47]
	v_mfma_f32_16x16x32_f16 v[40:43], v[140:143], v[156:159], v[40:43]
	v_mfma_f32_16x16x32_f16 v[28:31], v[132:135], v[164:167], v[28:31]
	v_mfma_f32_16x16x32_f16 v[24:27], v[140:143], v[164:167], v[24:27]
	v_mfma_f32_16x16x32_f16 v[12:15], v[132:135], v[172:175], v[12:15]
	v_mfma_f32_16x16x32_f16 v[8:11], v[140:143], v[172:175], v[8:11]
	s_barrier
	s_add_i32 m0, s31, 0x1c000
	s_nop 0
	global_load_lds_dwordx4 v206, s[96:97]
	s_add_i32 m0, s31, 0x1e000
	s_nop 0
	global_load_lds_dwordx4 v210, s[96:97]
	s_waitcnt vmcnt(6)
	s_barrier
	v_mfma_f32_16x16x32_f16 v[52:55], v[176:179], v[144:147], v[52:55]
	v_mfma_f32_16x16x32_f16 v[48:51], v[184:187], v[144:147], v[48:51]
	v_mfma_f32_16x16x32_f16 v[36:39], v[176:179], v[152:155], v[36:39]
	v_mfma_f32_16x16x32_f16 v[32:35], v[184:187], v[152:155], v[32:35]
	v_mfma_f32_16x16x32_f16 v[20:23], v[176:179], v[160:163], v[20:23]
	v_mfma_f32_16x16x32_f16 v[16:19], v[184:187], v[160:163], v[16:19]
	v_mfma_f32_16x16x32_f16 v[4:7], v[176:179], v[168:171], v[4:7]
	v_mfma_f32_16x16x32_f16 v[0:3], v[184:187], v[168:171], v[0:3]
	v_mfma_f32_16x16x32_f16 v[52:55], v[180:183], v[148:151], v[52:55]
	v_mfma_f32_16x16x32_f16 v[48:51], v[188:191], v[148:151], v[48:51]
	v_mfma_f32_16x16x32_f16 v[36:39], v[180:183], v[156:159], v[36:39]
	v_mfma_f32_16x16x32_f16 v[32:35], v[188:191], v[156:159], v[32:35]
	v_mfma_f32_16x16x32_f16 v[20:23], v[180:183], v[164:167], v[20:23]
	v_mfma_f32_16x16x32_f16 v[16:19], v[188:191], v[164:167], v[16:19]
	v_mfma_f32_16x16x32_f16 v[4:7], v[180:183], v[172:175], v[4:7]
	v_mfma_f32_16x16x32_f16 v[0:3], v[188:191], v[172:175], v[0:3]
	s_add_u32 s0, s0, 0x100
	s_addc_u32 s1, s1, 0
	s_add_u32 s27, s27, 0x100
	s_addc_u32 s33, s33, 0
	s_cmp_ge_u32 s38, s64
	s_mov_b32 s34, s38
	s_barrier
	s_cbranch_scc0 .LBB0_762
	s_setprio 0
	s_lshl_b32 s0, s84, 8
	s_or_b32 s27, s0, s65
	v_lshl_add_u32 v240, s30, 8, v200
	v_or_b32_e32 v216, s27, v202
	s_cmp_eq_u32 s93, 3
	s_cbranch_scc1 .Lst16_fast
	s_cmp_eq_u32 s93, 1
	s_cbranch_scc0 .Llora_no
	s_lshr_b32 s0, s84, 2
	s_cmp_lt_u32 s0, 2
	s_cbranch_scc1 .Llora_fast
